# row-norm wave reductions in phases 6 and 9: last four butterfly steps through DPP row rotations instead of ds_bpermute
# baseline (speedup 1.0000x reference)
; DI unsigned pk_bf16(float a, float b) { f32x2 v = {a, b}; return __builtin_bit_cast(unsigned, __builtin_convertvector(v, bf16v2)); }
; DI float wave_sum(float v) {
;     v += __shfl_xor(v, 32); v += __shfl_xor(v, 16); v += __shfl_xor(v, 8);
;     v += __shfl_xor(v, 4); v += __shfl_xor(v, 2); v += __shfl_xor(v, 1);
;     return v;
; }
; DI void phase6(const Params& p) {
;     ...
;         float ss2 = 0.f;
; #pragma unroll
;         for (int i = 0; i < 4; ++i) {
;             const f32x4 gg = *(const f32x4*)(gpost + i * 256 + lane * 4);
; #pragma unroll
;             for (int e = 0; e < 4; ++e) { xv[i][e] += mv[i][e] * rstd * gg[e]; ss2 += xv[i][e] * xv[i][e]; }
;         }
;         ss2 = wave_sum(ss2);
;         const float rstd2 = rsqrtf(ss2 * (1.f / 1024.f) + NORM_EPS);
; #pragma unroll
;         for (int i = 0; i < 4; ++i) {
;             const f32x4 gg = *(const f32x4*)(gffn + i * 256 + lane * 4);
;             u32x2 o; o.x = pk_bf16(xv[i][0] * rstd2 * gg[0], xv[i][1] * rstd2 * gg[1]); o.y = pk_bf16(xv[i][2] * rstd2 * gg[2], xv[i][3] * rstd2 * gg[3]);
;             *(u32x2*)(H + (size_t)row * 1024 + i * 256 + lane * 4) = o;
;         }
.LBB0_705:
	s_or_b64 exec, exec, s[4:5]
	v_mov_b32_e32 v39, v51
	v_mov_b32_e32 v41, v45
	v_mov_b32_e32 v45, v53
	v_mov_b32_e32 v33, v1
	v_mov_b32_e32 v35, v19
	v_mov_b32_e32 v43, v47
	v_pk_mul_f32 v[32:33], v[48:49], v[32:33] op_sel_hi:[0,1]
	v_pk_mul_f32 v[34:35], v[48:49], v[34:35] op_sel_hi:[0,1]
	v_pk_mul_f32 v[42:43], v[48:49], v[42:43] op_sel_hi:[0,1]
	v_mov_b32_e32 v37, v49
	v_pk_mul_f32 v[40:41], v[48:49], v[40:41] op_sel_hi:[0,1]
	v_pk_mul_f32 v[36:37], v[48:49], v[36:37] op_sel_hi:[0,1]
	v_pk_mul_f32 v[38:39], v[48:49], v[38:39] op_sel_hi:[0,1]
	v_mov_b32_e32 v47, v55
	v_pk_mul_f32 v[44:45], v[48:49], v[44:45] op_sel_hi:[0,1]
	v_pk_mul_f32 v[46:47], v[48:49], v[46:47] op_sel_hi:[0,1]
	v_add_co_u32_e64 v30, s[4:5], s16, v30
	v_add_u32_e32 v18, s6, v18
	s_nop 0
	v_addc_co_u32_e64 v31, s[4:5], 0, v31, s[4:5]
	v_lshl_add_u64 v[24:25], v[24:25], 0, s[8:9]
	v_lshl_add_u64 v[26:27], v[26:27], 0, s[10:11]
	v_lshl_add_u64 v[28:29], v[28:29], 0, s[12:13]
	v_pk_fma_f32 v[14:15], v[32:33], v[200:201], v[14:15]
	v_pk_fma_f32 v[16:17], v[34:35], v[202:203], v[16:17]
	v_pk_fma_f32 v[32:33], v[42:43], v[210:211], v[4:5]
	v_pk_mul_f32 v[4:5], v[14:15], v[14:15]
	v_pk_fma_f32 v[34:35], v[40:41], v[208:209], v[2:3]
	v_pk_mul_f32 v[2:3], v[16:17], v[16:17]
	v_add_f32_e32 v1, v4, v5
	v_pk_fma_f32 v[10:11], v[36:37], v[204:205], v[10:11]
	v_add_f32_e32 v1, v2, v1
	v_pk_fma_f32 v[12:13], v[38:39], v[206:207], v[12:13]
	v_pk_mul_f32 v[38:39], v[10:11], v[10:11]
	v_add_f32_e32 v1, v3, v1
	v_add_f32_e32 v1, v38, v1
	v_pk_mul_f32 v[36:37], v[12:13], v[12:13]
	v_add_f32_e32 v1, v39, v1
	v_add_f32_e32 v1, v36, v1
	v_pk_mul_f32 v[42:43], v[34:35], v[34:35]
	v_add_f32_e32 v1, v37, v1
	v_add_f32_e32 v1, v42, v1
	v_pk_mul_f32 v[40:41], v[32:33], v[32:33]
	v_add_f32_e32 v1, v43, v1
	v_pk_fma_f32 v[6:7], v[44:45], v[212:213], v[6:7]
	v_add_f32_e32 v1, v40, v1
	v_pk_fma_f32 v[8:9], v[46:47], v[214:215], v[8:9]
	v_pk_mul_f32 v[46:47], v[6:7], v[6:7]
	v_add_f32_e32 v1, v41, v1
	v_add_f32_e32 v1, v46, v1
	v_pk_mul_f32 v[44:45], v[8:9], v[8:9]
	v_add_f32_e32 v1, v47, v1
	v_add_f32_e32 v1, v44, v1
	v_add_f32_e32 v1, v45, v1
	ds_bpermute_b32 v2, v57, v1
	s_waitcnt lgkmcnt(0)
	v_add_f32_e32 v1, v1, v2
	ds_bpermute_b32 v2, v58, v1
	s_waitcnt lgkmcnt(0)
	v_add_f32_e32 v1, v1, v2
	s_nop 1
	v_add_f32_dpp v1, v1, v1 row_ror:8 row_mask:0xf bank_mask:0xf
	s_nop 1
	v_add_f32_dpp v1, v1, v1 row_ror:4 row_mask:0xf bank_mask:0xf
	s_nop 1
	v_add_f32_dpp v1, v1, v1 row_ror:2 row_mask:0xf bank_mask:0xf
	s_nop 1
	v_add_f32_dpp v1, v1, v1 row_ror:1 row_mask:0xf bank_mask:0xf
	v_fmamk_f32 v1, v1, 0x3a800000, v63
	v_mul_f32_e32 v2, 0x4b800000, v1
	v_cmp_gt_f32_e32 vcc, s7, v1
	s_nop 1
	v_cndmask_b32_e32 v1, v1, v2, vcc
	v_rsq_f32_e32 v1, v1
	s_nop 0
	v_mul_f32_e32 v2, 0x45800000, v1
	v_cndmask_b32_e32 v36, v1, v2, vcc
	v_pk_mul_f32 v[2:3], v[14:15], v[36:37] op_sel_hi:[1,0]
	v_pk_mul_f32 v[4:5], v[16:17], v[36:37] op_sel_hi:[1,0]
	v_pk_mul_f32 v[2:3], v[216:217], v[2:3]
	v_pk_mul_f32 v[4:5], v[218:219], v[4:5]
	v_cvt_pk_bf16_f32 v2, v2, v3
	v_cvt_pk_bf16_f32 v3, v4, v5
	global_store_dwordx2 v[30:31], v[2:3], off offset:2048
	v_pk_mul_f32 v[10:11], v[10:11], v[36:37] op_sel_hi:[1,0]
	v_pk_mul_f32 v[12:13], v[12:13], v[36:37] op_sel_hi:[1,0]
	v_pk_mul_f32 v[6:7], v[6:7], v[36:37] op_sel_hi:[1,0]
	v_pk_mul_f32 v[8:9], v[8:9], v[36:37] op_sel_hi:[1,0]
	v_cmp_lt_i32_e32 vcc, s17, v18
	s_or_b64 s[14:15], vcc, s[14:15]
	v_pk_mul_f32 v[2:3], v[220:221], v[10:11]
	v_pk_mul_f32 v[4:5], v[222:223], v[12:13]
	v_cvt_pk_bf16_f32 v2, v2, v3
	v_cvt_pk_bf16_f32 v3, v4, v5
	global_store_dwordx2 v[30:31], v[2:3], off offset:2560
	v_pk_mul_f32 v[10:11], v[34:35], v[36:37] op_sel_hi:[1,0]
	v_pk_mul_f32 v[12:13], v[32:33], v[36:37] op_sel_hi:[1,0]
	v_pk_mul_f32 v[2:3], v[224:225], v[10:11]
	v_pk_mul_f32 v[4:5], v[226:227], v[12:13]
	v_cvt_pk_bf16_f32 v2, v2, v3
	v_cvt_pk_bf16_f32 v3, v4, v5
	global_store_dwordx2 v[30:31], v[2:3], off offset:3072
	s_nop 1
	v_pk_mul_f32 v[2:3], v[228:229], v[6:7]
	v_pk_mul_f32 v[4:5], v[230:231], v[8:9]
	v_cvt_pk_bf16_f32 v2, v2, v3
	v_cvt_pk_bf16_f32 v3, v4, v5
	global_store_dwordx2 v[30:31], v[2:3], off offset:3584
	s_andn2_b64 exec, exec, s[14:15]
	s_cbranch_execz .LBB0_708

; DI float bflo(unsigned u) { return __uint_as_float(u << 16); }
; DI float bfhi(unsigned u) { return __uint_as_float(u & 0xffff0000u); }
; DI float wave_sum(float v) {
;     v += __shfl_xor(v, 32); v += __shfl_xor(v, 16); v += __shfl_xor(v, 8);
;     v += __shfl_xor(v, 4); v += __shfl_xor(v, 2); v += __shfl_xor(v, 1);
;     return v;
; }
; DI void phase6(const Params& p) {
;     ...
;             const u32x2 u = *(const u32x2*)(MIX + (size_t)row * 1024 + i * 256 + lane * 4);
;             mv[i][0] = bflo(u.x); mv[i][1] = bfhi(u.x); mv[i][2] = bflo(u.y); mv[i][3] = bfhi(u.y);
;             xv[i] = *(const f32x4*)(x + (size_t)row * 1024 + i * 256 + lane * 4);
;             ss += mv[i][0] * mv[i][0] + mv[i][1] * mv[i][1] + mv[i][2] * mv[i][2] + mv[i][3] * mv[i][3];
;         }
;         ss = wave_sum(ss);
;         const float rstd = rsqrtf(ss * (1.f / 1024.f) + NORM_EPS);
;         if (lane == 0) RSTD[row] = rstd;
.Lp6_nopf:
	s_or_b64 exec, exec, s[98:99]
	v_and_b32_e32 v1, 0xffff0000, v34
	v_lshlrev_b32_e32 v36, 16, v38
	v_and_b32_e32 v49, 0xffff0000, v38
	v_and_b32_e32 v45, 0xffff0000, v42
	v_mov_b32_e32 v48, v1
	v_lshlrev_b32_e32 v32, 16, v34
	v_lshlrev_b32_e32 v38, 16, v39
	v_lshlrev_b32_e32 v44, 16, v54
	v_and_b32_e32 v53, 0xffff0000, v54
	v_mov_b32_e32 v33, v36
	v_mov_b32_e32 v52, v45
	v_pk_mul_f32 v[64:65], v[48:49], v[48:49]
	v_lshlrev_b32_e32 v34, 16, v35
	v_and_b32_e32 v19, 0xffff0000, v35
	v_lshlrev_b32_e32 v40, 16, v42
	v_lshlrev_b32_e32 v46, 16, v55
	v_mov_b32_e32 v35, v38
	v_mov_b32_e32 v41, v44
	v_pk_mul_f32 v[66:67], v[52:53], v[52:53]
	v_pk_fma_f32 v[64:65], v[32:33], v[32:33], v[64:65]
	v_and_b32_e32 v51, 0xffff0000, v39
	v_lshlrev_b32_e32 v42, 16, v43
	v_and_b32_e32 v47, 0xffff0000, v43
	v_mov_b32_e32 v50, v19
	v_mov_b32_e32 v43, v46
	v_pk_fma_f32 v[66:67], v[40:41], v[40:41], v[66:67]
	v_pk_fma_f32 v[64:65], v[34:35], v[34:35], v[64:65]
	v_and_b32_e32 v55, 0xffff0000, v55
	v_mov_b32_e32 v54, v47
	v_pk_fma_f32 v[66:67], v[42:43], v[42:43], v[66:67]
	v_pk_fma_f32 v[64:65], v[50:51], v[50:51], v[64:65]
	v_pk_fma_f32 v[66:67], v[54:55], v[54:55], v[66:67]
	v_add_f32_e32 v33, v64, v65
	v_add_f32_e32 v33, v33, v66
	v_add_f32_e32 v33, v33, v67
	ds_bpermute_b32 v35, v57, v33
	s_waitcnt lgkmcnt(0)
	v_add_f32_e32 v33, v33, v35
	ds_bpermute_b32 v35, v58, v33
	s_waitcnt lgkmcnt(0)
	v_add_f32_e32 v33, v33, v35
	s_nop 1
	v_add_f32_dpp v33, v33, v33 row_ror:8 row_mask:0xf bank_mask:0xf
	s_nop 1
	v_add_f32_dpp v33, v33, v33 row_ror:4 row_mask:0xf bank_mask:0xf
	s_nop 1
	v_add_f32_dpp v33, v33, v33 row_ror:2 row_mask:0xf bank_mask:0xf
	s_nop 1
	v_add_f32_dpp v33, v33, v33 row_ror:1 row_mask:0xf bank_mask:0xf
	v_fmamk_f32 v33, v33, 0x3a800000, v63
	v_mul_f32_e32 v35, 0x4b800000, v33
	v_cmp_gt_f32_e32 vcc, s7, v33
	s_nop 1
	v_cndmask_b32_e32 v33, v33, v35, vcc
	v_rsq_f32_e32 v33, v33
	s_nop 0
	v_mul_f32_e32 v35, 0x45800000, v33
	v_cndmask_b32_e32 v48, v33, v35, vcc
	s_and_saveexec_b64 s[4:5], s[0:1]
	s_cbranch_execz .LBB0_705
	v_lshl_add_u64 v[64:65], s[88:89], 0, v[24:25]
	global_store_dword v[64:65], v48, off
	s_branch .LBB0_705

; DI float bflo(unsigned u) { return __uint_as_float(u << 16); }
; DI float bfhi(unsigned u) { return __uint_as_float(u & 0xffff0000u); }
; DI float wave_sum(float v) {
;     v += __shfl_xor(v, 32); v += __shfl_xor(v, 16); v += __shfl_xor(v, 8);
;     v += __shfl_xor(v, 4); v += __shfl_xor(v, 2); v += __shfl_xor(v, 1);
;     return v;
; }
; DI void phase9(const Params& p) {
;     ...
;         for (int i = 0; i < 4; ++i) {
;             const u32x2 u = *(const u32x2*)(F + (size_t)row * 1024 + i * 256 + lane * 4);
;             fv[i][0] = bflo(u.x); fv[i][1] = bfhi(u.x); fv[i][2] = bflo(u.y); fv[i][3] = bfhi(u.y);
;             const u32x2 um = *(const u32x2*)(MIX + (size_t)row * 1024 + i * 256 + lane * 4);
;             mv[i][0] = bflo(um.x); mv[i][1] = bfhi(um.x); mv[i][2] = bflo(um.y); mv[i][3] = bfhi(um.y);
;             ss += fv[i][0] * fv[i][0] + fv[i][1] * fv[i][1] + fv[i][2] * fv[i][2] + fv[i][3] * fv[i][3];
;         }
;         ss = wave_sum(ss);
;         const float rstd = rsqrtf(ss * (1.f / 1024.f) + NORM_EPS);
;         const float rstd1 = RSTD[row];
; #pragma unroll
;         for (int i = 0; i < 4; ++i) {
;             const f32x4 ga = *(const f32x4*)(g1 + i * 256 + lane * 4);
;             const f32x4 gb = *(const f32x4*)(g2 + i * 256 + lane * 4);
;             f32x4 xv = *(const f32x4*)(x + (size_t)row * 1024 + i * 256 + lane * 4);
; #pragma unroll
;             for (int e = 0; e < 4; ++e) { xv[e] += mv[i][e] * rstd1 * ga[e]; xv[e] += fv[i][e] * rstd * gb[e]; }
;             *(f32x4*)(p.out + (size_t)row * 1024 + i * 256 + lane * 4) = xv;
;         }
.Lp9_nopf:
	s_or_b64 exec, exec, s[98:99]
	v_and_b32_e32 v35, 0xffff0000, v36
	v_and_b32_e32 v57, 0xffff0000, v44
	v_lshlrev_b32_e32 v34, 16, v36
	v_lshlrev_b32_e32 v56, 16, v44
	v_and_b32_e32 v59, 0xffff0000, v46
	v_and_b32_e32 v61, 0xffff0000, v48
	v_lshlrev_b32_e32 v62, 16, v40
	v_and_b32_e32 v63, 0xffff0000, v40
	v_mov_b32_e32 v66, v35
	v_mov_b32_e32 v67, v57
	v_lshlrev_b32_e32 v36, 16, v37
	v_lshlrev_b32_e32 v44, 16, v45
	v_lshlrev_b32_e32 v58, 16, v46
	v_lshlrev_b32_e32 v60, 16, v48
	v_lshlrev_b32_e32 v40, 16, v41
	v_and_b32_e32 v41, 0xffff0000, v41
	v_mov_b32_e32 v64, v34
	v_mov_b32_e32 v65, v56
	v_mov_b32_e32 v74, v59
	v_mov_b32_e32 v75, v61
	v_pk_mul_f32 v[62:63], v[42:43], v[62:63] op_sel_hi:[0,1]
	v_pk_mul_f32 v[66:67], v[66:67], v[66:67]
	v_and_b32_e32 v37, 0xffff0000, v37
	v_and_b32_e32 v45, 0xffff0000, v45
	v_lshlrev_b32_e32 v46, 16, v47
	v_lshlrev_b32_e32 v48, 16, v49
	v_mov_b32_e32 v68, v36
	v_mov_b32_e32 v69, v44
	v_mov_b32_e32 v72, v58
	v_mov_b32_e32 v73, v60
	v_pk_mul_f32 v[40:41], v[42:43], v[40:41] op_sel_hi:[0,1]
	v_pk_mul_f32 v[74:75], v[74:75], v[74:75]
	v_pk_fma_f32 v[22:23], v[62:63], v[200:201], v[30:31]
	v_pk_fma_f32 v[30:31], v[64:65], v[64:65], v[66:67]
	v_and_b32_e32 v47, 0xffff0000, v47
	v_and_b32_e32 v49, 0xffff0000, v49
	v_mov_b32_e32 v70, v37
	v_mov_b32_e32 v71, v45
	v_mov_b32_e32 v76, v46
	v_mov_b32_e32 v77, v48
	v_pk_fma_f32 v[24:25], v[40:41], v[202:203], v[32:33]
	v_pk_fma_f32 v[32:33], v[72:73], v[72:73], v[74:75]
	v_pk_fma_f32 v[30:31], v[68:69], v[68:69], v[30:31]
	v_mov_b32_e32 v78, v47
	v_mov_b32_e32 v79, v49
	v_pk_fma_f32 v[32:33], v[76:77], v[76:77], v[32:33]
	v_pk_fma_f32 v[30:31], v[70:71], v[70:71], v[30:31]
	v_pk_fma_f32 v[32:33], v[78:79], v[78:79], v[32:33]
	v_add_f32_e32 v21, v30, v31
	v_add_f32_e32 v21, v21, v32
	v_add_f32_e32 v21, v21, v33
	ds_bpermute_b32 v30, v15, v21
	s_waitcnt lgkmcnt(0)
	v_add_f32_e32 v21, v21, v30
	ds_bpermute_b32 v30, v16, v21
	s_waitcnt lgkmcnt(0)
	v_add_f32_e32 v21, v21, v30
	s_nop 1
	v_add_f32_dpp v21, v21, v21 row_ror:8 row_mask:0xf bank_mask:0xf
	s_nop 1
	v_add_f32_dpp v21, v21, v21 row_ror:4 row_mask:0xf bank_mask:0xf
	s_nop 1
	v_add_f32_dpp v21, v21, v21 row_ror:2 row_mask:0xf bank_mask:0xf
	s_nop 1
	v_add_f32_dpp v21, v21, v21 row_ror:1 row_mask:0xf bank_mask:0xf
	v_fmamk_f32 v21, v21, 0x3a800000, v1
	v_mul_f32_e32 v30, 0x4b800000, v21
	v_cmp_gt_f32_e32 vcc, s3, v21
	s_nop 1
	v_cndmask_b32_e32 v21, v21, v30, vcc
	v_rsq_f32_e32 v21, v21
	s_nop 0
	v_mul_f32_e32 v30, 0x45800000, v21
	v_cndmask_b32_e32 v40, v21, v30, vcc
	v_pk_mul_f32 v[30:31], v[40:41], v[34:35] op_sel_hi:[0,1]
	v_pk_mul_f32 v[32:33], v[40:41], v[36:37] op_sel_hi:[0,1]
	v_pk_fma_f32 v[22:23], v[216:217], v[30:31], v[22:23]
	v_pk_fma_f32 v[24:25], v[218:219], v[32:33], v[24:25]
	global_store_dwordx4 v[12:13], v[22:25], off
	v_lshlrev_b32_e32 v34, 16, v50
	v_and_b32_e32 v35, 0xffff0000, v50
	v_lshlrev_b32_e32 v36, 16, v51
	v_and_b32_e32 v37, 0xffff0000, v51
	v_pk_mul_f32 v[34:35], v[42:43], v[34:35] op_sel_hi:[0,1]
	v_pk_mul_f32 v[36:37], v[42:43], v[36:37] op_sel_hi:[0,1]
	v_pk_mul_f32 v[50:51], v[40:41], v[56:57] op_sel_hi:[0,1]
	v_pk_mul_f32 v[44:45], v[40:41], v[44:45] op_sel_hi:[0,1]
	v_pk_mul_f32 v[46:47], v[40:41], v[46:47] op_sel_hi:[0,1]
	v_cmp_lt_i32_e32 vcc, s12, v0
	s_or_b64 s[10:11], vcc, s[10:11]
	v_pk_fma_f32 v[22:23], v[34:35], v[204:205], v[80:81]
	v_pk_fma_f32 v[24:25], v[36:37], v[206:207], v[82:83]
	v_pk_fma_f32 v[22:23], v[220:221], v[50:51], v[22:23]
	v_pk_fma_f32 v[24:25], v[222:223], v[44:45], v[24:25]
	global_store_dwordx4 v[12:13], v[22:25], off offset:1024
	v_lshlrev_b32_e32 v34, 16, v52
	v_and_b32_e32 v35, 0xffff0000, v52
	v_lshlrev_b32_e32 v36, 16, v53
	v_and_b32_e32 v37, 0xffff0000, v53
	v_pk_mul_f32 v[34:35], v[42:43], v[34:35] op_sel_hi:[0,1]
	v_pk_mul_f32 v[36:37], v[42:43], v[36:37] op_sel_hi:[0,1]
	v_pk_mul_f32 v[44:45], v[40:41], v[58:59] op_sel_hi:[0,1]
	v_pk_fma_f32 v[22:23], v[34:35], v[208:209], v[84:85]
	v_pk_fma_f32 v[24:25], v[36:37], v[210:211], v[86:87]
	v_pk_fma_f32 v[22:23], v[224:225], v[44:45], v[22:23]
	v_pk_fma_f32 v[24:25], v[226:227], v[46:47], v[24:25]
	global_store_dwordx4 v[12:13], v[22:25], off offset:2048
	v_lshlrev_b32_e32 v34, 16, v54
	v_and_b32_e32 v35, 0xffff0000, v54
	v_lshlrev_b32_e32 v36, 16, v55
	v_and_b32_e32 v37, 0xffff0000, v55
	v_pk_mul_f32 v[34:35], v[42:43], v[34:35] op_sel_hi:[0,1]
	v_pk_mul_f32 v[36:37], v[42:43], v[36:37] op_sel_hi:[0,1]
	v_pk_mul_f32 v[38:39], v[40:41], v[60:61] op_sel_hi:[0,1]
	v_pk_mul_f32 v[40:41], v[40:41], v[48:49] op_sel_hi:[0,1]
	v_pk_fma_f32 v[22:23], v[34:35], v[212:213], v[88:89]
	v_pk_fma_f32 v[24:25], v[36:37], v[214:215], v[90:91]
	v_pk_fma_f32 v[22:23], v[38:39], v[228:229], v[22:23]
	v_pk_fma_f32 v[24:25], v[40:41], v[230:231], v[24:25]
	global_store_dwordx4 v[12:13], v[22:25], off offset:3072
	s_andn2_b64 exec, exec, s[10:11]
	s_cbranch_execnz .LBB0_907
